# attention: waves 4-7 (the prioritized half) issue the whole tile LDS-DMA, waves 0-3 none; safer V ring register order; plus previous attention/P0a/cg changes
# speedup vs baseline: 1.0187x; 1.0066x over previous
;     ...
;     f32x16 pA0, pA1, pB0, pB1; float alA, alB; bf16x8 pa0, pa1, pa2, pa3;
;     int sp = 0, sc_ = 1, sn = 2;
.LBB0_695:
	s_lshl_b32 s43, s34, 13
	s_mov_b32 s42, s38
	v_lshl_add_u32 v185, s42, 13, v184
	ds_read_b128 v[112:115], v185 offset:49152
	ds_read_b128 v[186:189], v185 offset:49664
	s_mov_b32 s38, s44
	s_cmp_lt_i32 s18, 4
	s_cbranch_scc1 .Lattn_nodma_Lattn_m0_res1
	s_add_i32 s98, s43, s39
	s_mov_b32 m0, s98
	s_mov_b32 s100, 0xffffffc0
	s_mov_b32 s101, -1
	global_load_lds_dwordx4 v[172:173], off
	s_addk_i32 s98, 0xf000
	s_mov_b32 m0, s98
	v_lshl_add_u64 v[212:213], v[172:173], 0, s[100:101]
	global_load_lds_dwordx4 v[212:213], off
	s_lshl_b32 s98, s34, 14
	s_add_i32 s99, s98, s24
	s_mov_b32 m0, s99
	v_lshl_add_u64 v[212:213], s[68:69], 0, v[166:167]
	global_load_lds_dwordx4 v[212:213], off
	s_add_u32 s100, s68, 0xffff8000
	s_addc_u32 s101, s69, -1
	s_addk_i32 s99, 0xf000
	s_mov_b32 m0, s99
	v_lshl_add_u64 v[214:215], s[100:101], 0, v[166:167]
	global_load_lds_dwordx4 v[214:215], off
	s_add_i32 s98, s98, s25
	s_mov_b32 m0, s98
	v_lshl_add_u64 v[212:213], s[68:69], 0, v[170:171]
	global_load_lds_dwordx4 v[212:213], off
	s_addk_i32 s98, 0xf000
	s_mov_b32 m0, s98
	v_lshl_add_u64 v[214:215], s[100:101], 0, v[170:171]
	global_load_lds_dwordx4 v[214:215], off
.Lattn_nodma_Lattn_m0_res1:
	s_waitcnt lgkmcnt(1)
	v_mfma_f32_32x32x16_bf16 v[128:143], v[112:115], v[156:159], v[64:79]
	ds_read_b128 v[190:193], v185 offset:51200
	ds_read_b128 v[194:197], v185 offset:51712
	v_add_f32_e32 v116, v98, v96
	v_add_f32_e32 v117, v99, v97
	v_cvt_pk_bf16_f32 v96, v96, v97
	v_cvt_pk_bf16_f32 v97, v98, v99
	v_cvt_pk_bf16_f32 v98, v100, v101
	v_cvt_pk_bf16_f32 v99, v102, v103
	v_add_f32_e32 v100, v100, v116
	v_add_f32_e32 v101, v101, v117
	s_waitcnt lgkmcnt(2)
	v_mfma_f32_32x32x16_bf16 v[112:127], v[186:189], v[156:159], v[64:79]
	v_add_f32_e32 v100, v102, v100
	v_add_f32_e32 v101, v103, v101
	s_waitcnt lgkmcnt(1)
	v_mfma_f32_32x32x16_bf16 v[128:143], v[190:193], v[152:155], v[128:143]
	ds_read_b128 v[186:189], v185 offset:53248
	ds_read_b128 v[198:201], v185 offset:53760
	v_add_f32_e32 v100, v104, v100
	v_add_f32_e32 v101, v105, v101
	v_add_f32_e32 v202, v106, v100
	v_add_f32_e32 v203, v107, v101
	v_cvt_pk_bf16_f32 v100, v104, v105
	v_cvt_pk_bf16_f32 v101, v106, v107
	v_cvt_pk_bf16_f32 v102, v108, v109
	v_cvt_pk_bf16_f32 v103, v110, v111
	s_waitcnt lgkmcnt(2)
	v_mfma_f32_32x32x16_bf16 v[112:127], v[194:197], v[152:155], v[112:127]
	v_add_f32_e32 v104, v108, v202
	v_add_f32_e32 v105, v109, v203
	v_add_f32_e32 v190, v110, v104
	v_add_f32_e32 v191, v111, v105
	s_waitcnt lgkmcnt(1)
	v_mfma_f32_32x32x16_bf16 v[128:143], v[186:189], v[148:151], v[128:143]
	ds_read_b128 v[104:107], v185 offset:55296
	ds_read_b128 v[108:111], v185 offset:55808
	v_add_f32_e32 v185, v80, v190
	v_add_f32_e32 v190, v81, v191
	v_add_f32_e32 v185, v82, v185
	v_add_f32_e32 v190, v83, v190
	v_cvt_pk_bf16_f32 v80, v80, v81
	v_cvt_pk_bf16_f32 v81, v82, v83
	v_cvt_pk_bf16_f32 v82, v84, v85
	v_cvt_pk_bf16_f32 v83, v86, v87
	s_waitcnt lgkmcnt(2)
	v_mfma_f32_32x32x16_bf16 v[112:127], v[198:201], v[148:151], v[112:127]
	s_lshl_b32 s44, s38, 14
	v_add_u32_e32 v189, s44, v183
	ds_read_b64_tr_b16 v[194:195], v189 offset:0
	ds_read_b64_tr_b16 v[196:197], v189 offset:0x800
	ds_read_b64_tr_b16 v[212:213], v189 offset:0x1000
	ds_read_b64_tr_b16 v[214:215], v189 offset:0x1800
	ds_read_b64_tr_b16 v[216:217], v189 offset:0x2000
	ds_read_b64_tr_b16 v[218:219], v189 offset:0x2800
	v_add_f32_e32 v84, v84, v185
	v_add_f32_e32 v85, v85, v190
	v_add_f32_e32 v84, v86, v84
	v_add_f32_e32 v85, v87, v85
	s_waitcnt lgkmcnt(7)
	v_mfma_f32_32x32x16_bf16 v[128:143], v[104:107], v[144:147], v[128:143]
	ds_read_b64_tr_b16 v[198:199], v189 offset:0x3000
	ds_read_b64_tr_b16 v[200:201], v189 offset:0x3800
	ds_read_b64_tr_b16 v[190:191], v189 offset:0x200
	ds_read_b64_tr_b16 v[192:193], v189 offset:0xa00
	v_add_f32_e32 v84, v88, v84
	v_add_f32_e32 v85, v89, v85
	v_add_f32_e32 v185, v90, v84
	v_add_f32_e32 v186, v91, v85
	v_cvt_pk_bf16_f32 v84, v88, v89
	v_cvt_pk_bf16_f32 v85, v90, v91
	v_cvt_pk_bf16_f32 v86, v92, v93
	v_cvt_pk_bf16_f32 v87, v94, v95
	s_waitcnt lgkmcnt(10)
	v_mfma_f32_32x32x16_bf16 v[112:127], v[108:111], v[144:147], v[112:127]
	v_add_f32_e32 v88, v92, v185
	v_add_f32_e32 v89, v93, v186
	v_add_f32_e32 v88, v94, v88
	v_add_f32_e32 v89, v95, v89
	ds_read_b64_tr_b16 v[220:221], v189 offset:0x1200
	ds_read_b64_tr_b16 v[222:223], v189 offset:0x1a00
	ds_read_b64_tr_b16 v[224:225], v189 offset:0x2200
	ds_read_b64_tr_b16 v[226:227], v189 offset:0x2a00
	s_waitcnt lgkmcnt(12)
	v_mfma_f32_32x32x16_bf16 v[48:63], v[96:99], v[194:197], v[48:63]
	v_max_f32_e32 v90, v128, v129
	v_max3_f32 v91, v131, v132, v133
	v_max3_f32 v90, v90, v130, v134
	v_max3_f32 v91, v91, v136, v137
	ds_read_b64_tr_b16 v[194:195], v189 offset:0x3200
	ds_read_b64_tr_b16 v[196:197], v189 offset:0x3a00
	s_waitcnt lgkmcnt(12)
	v_mfma_f32_32x32x16_bf16 v[48:63], v[100:103], v[212:215], v[48:63]
	v_max3_f32 v90, v90, v135, v138
	v_max3_f32 v91, v91, v140, v141
	v_max3_f32 v90, v90, v139, v142
	v_max3_f32 v90, v90, v143, v91
	v_add_f32_e32 v186, v88, v89
	v_mov_b32_e32 v187, v186
	ds_read_b64_tr_b16 v[212:213], v189 offset:0x400
	ds_read_b64_tr_b16 v[214:215], v189 offset:0xc00
	s_waitcnt lgkmcnt(12)
	v_mfma_f32_32x32x16_bf16 v[48:63], v[80:83], v[216:219], v[48:63]
	v_max3_f32 v88, v112, v113, v114
	v_max3_f32 v89, v115, v116, v117
	v_max3_f32 v88, v88, v118, v119
	v_max3_f32 v89, v89, v120, v121
	v_permlane32_swap_b32_e32 v186, v187
	v_max3_f32 v88, v88, v122, v123
	ds_read_b64_tr_b16 v[216:217], v189 offset:0x1400
	ds_read_b64_tr_b16 v[218:219], v189 offset:0x1c00
	s_waitcnt lgkmcnt(12)
	v_mfma_f32_32x32x16_bf16 v[48:63], v[84:87], v[198:201], v[48:63]
	v_max3_f32 v89, v89, v124, v125
	v_max3_f32 v88, v88, v126, v127
	v_max3_f32 v88, v90, v88, v89
	v_mov_b32_e32 v89, v88
	ds_read_b64_tr_b16 v[198:199], v189 offset:0x2400
	ds_read_b64_tr_b16 v[200:201], v189 offset:0x2c00
	s_waitcnt lgkmcnt(12)
	v_mfma_f32_32x32x16_bf16 v[32:47], v[96:99], v[190:193], v[32:47]
	v_permlane32_swap_b32_e32 v88, v89
	v_max_f32_e32 v88, v88, v89
	v_cmp_lt_f32_e32 vcc, s47, v88
	v_mov_b32_e32 v188, 1.0
	s_cbranch_vccnz .LBB0_707
;     ...
;     f32x16 pA0, pA1, pB0, pB1; float alA, alB; bf16x8 pa0, pa1, pa2, pa3;
;     int sp = 0, sc_ = 1, sn = 2;
.Lattn_m0_res1:
	ds_read_b64_tr_b16 v[190:191], v189 offset:0x3400
	ds_read_b64_tr_b16 v[192:193], v189 offset:0x3c00
	s_waitcnt lgkmcnt(12)
	v_mfma_f32_32x32x16_bf16 v[32:47], v[100:103], v[220:223], v[32:47]
	v_exp_f32_e32 v128, v128
	v_exp_f32_e32 v129, v129
	v_exp_f32_e32 v130, v130
	ds_read_b64_tr_b16 v[220:221], v189 offset:0x600
	ds_read_b64_tr_b16 v[222:223], v189 offset:0xe00
	s_waitcnt lgkmcnt(12)
	v_mfma_f32_32x32x16_bf16 v[32:47], v[80:83], v[224:227], v[32:47]
	v_exp_f32_e32 v131, v131
	v_exp_f32_e32 v132, v132
	v_exp_f32_e32 v133, v133
	ds_read_b64_tr_b16 v[224:225], v189 offset:0x1600
	ds_read_b64_tr_b16 v[226:227], v189 offset:0x1e00
	s_waitcnt lgkmcnt(12)
	v_mfma_f32_32x32x16_bf16 v[32:47], v[84:87], v[194:197], v[32:47]
	v_exp_f32_e32 v134, v134
	v_exp_f32_e32 v135, v135
	v_exp_f32_e32 v136, v136
	ds_read_b64_tr_b16 v[194:195], v189 offset:0x2600
	ds_read_b64_tr_b16 v[196:197], v189 offset:0x2e00
	s_waitcnt lgkmcnt(12)
	v_mfma_f32_32x32x16_bf16 v[16:31], v[96:99], v[212:215], v[16:31]
	v_exp_f32_e32 v137, v137
	v_exp_f32_e32 v138, v138
	v_exp_f32_e32 v139, v139
	ds_read_b64_tr_b16 v[212:213], v189 offset:0x3600
	ds_read_b64_tr_b16 v[214:215], v189 offset:0x3e00
	s_waitcnt lgkmcnt(12)
	v_mfma_f32_32x32x16_bf16 v[16:31], v[100:103], v[216:219], v[16:31]
	v_exp_f32_e32 v140, v140
	v_exp_f32_e32 v141, v141
	v_exp_f32_e32 v142, v142
	s_waitcnt lgkmcnt(10)
	v_mfma_f32_32x32x16_bf16 v[16:31], v[80:83], v[198:201], v[16:31]
	v_exp_f32_e32 v143, v143
	v_exp_f32_e32 v112, v112
	v_exp_f32_e32 v113, v113
	s_waitcnt lgkmcnt(8)
	v_mfma_f32_32x32x16_bf16 v[16:31], v[84:87], v[190:193], v[16:31]
	v_exp_f32_e32 v114, v114
	v_exp_f32_e32 v115, v115
	v_exp_f32_e32 v116, v116
	s_waitcnt lgkmcnt(6)
	v_mfma_f32_32x32x16_bf16 v[0:15], v[96:99], v[220:223], v[0:15]
	v_exp_f32_e32 v117, v117
	v_exp_f32_e32 v118, v118
	v_exp_f32_e32 v119, v119
	s_waitcnt lgkmcnt(4)
	v_mfma_f32_32x32x16_bf16 v[0:15], v[100:103], v[224:227], v[0:15]
	v_exp_f32_e32 v120, v120
	v_exp_f32_e32 v121, v121
	v_exp_f32_e32 v122, v122
	s_waitcnt lgkmcnt(2)
	v_mfma_f32_32x32x16_bf16 v[0:15], v[80:83], v[194:197], v[0:15]
	v_exp_f32_e32 v123, v123
	v_exp_f32_e32 v124, v124
	v_exp_f32_e32 v125, v125
	s_waitcnt lgkmcnt(0)
	v_mfma_f32_32x32x16_bf16 v[0:15], v[84:87], v[212:215], v[0:15]
	v_exp_f32_e32 v126, v126
	v_exp_f32_e32 v127, v127
	v_cmp_gt_f32_e32 vcc, 1.0, v188
	s_cbranch_vccz .LBB0_700
	s_and_saveexec_b64 s[70:71], s[0:1]
	ds_write_b32 v177, v188 offset:128
	s_or_b64 exec, exec, s[70:71]
	s_waitcnt lgkmcnt(0)
	v_add_u32_e32 v92, s19, v168
	ds_read_b128 v[80:83], v92 offset:224
	ds_read_b128 v[84:87], v92 offset:192
	ds_read_b128 v[88:91], v92 offset:160
	ds_read_b128 v[92:95], v92 offset:128
	s_waitcnt lgkmcnt(3)
	v_pk_mul_f32 v[60:61], v[60:61], v[80:81]
	s_waitcnt lgkmcnt(2)
	v_pk_mul_f32 v[56:57], v[56:57], v[84:85]
	s_waitcnt lgkmcnt(1)
	v_pk_mul_f32 v[52:53], v[52:53], v[88:89]
	v_pk_mul_f32 v[62:63], v[62:63], v[82:83]
	v_pk_mul_f32 v[58:59], v[58:59], v[86:87]
	v_pk_mul_f32 v[54:55], v[54:55], v[90:91]
	s_waitcnt lgkmcnt(0)
	v_pk_mul_f32 v[50:51], v[50:51], v[94:95]
	v_pk_mul_f32 v[48:49], v[48:49], v[92:93]
	v_pk_mul_f32 v[44:45], v[44:45], v[80:81]
	v_pk_mul_f32 v[40:41], v[40:41], v[84:85]
	v_pk_mul_f32 v[36:37], v[36:37], v[88:89]
	v_pk_mul_f32 v[46:47], v[46:47], v[82:83]
	v_pk_mul_f32 v[42:43], v[42:43], v[86:87]
	v_pk_mul_f32 v[38:39], v[38:39], v[90:91]
	v_pk_mul_f32 v[34:35], v[34:35], v[94:95]
	v_pk_mul_f32 v[32:33], v[32:33], v[92:93]
	v_pk_mul_f32 v[28:29], v[28:29], v[80:81]
	v_pk_mul_f32 v[24:25], v[24:25], v[84:85]
	v_pk_mul_f32 v[20:21], v[20:21], v[88:89]
	v_pk_mul_f32 v[30:31], v[30:31], v[82:83]
	v_pk_mul_f32 v[26:27], v[26:27], v[86:87]
	v_pk_mul_f32 v[22:23], v[22:23], v[90:91]
	v_pk_mul_f32 v[18:19], v[18:19], v[94:95]
	v_pk_mul_f32 v[16:17], v[16:17], v[92:93]
	v_pk_mul_f32 v[12:13], v[12:13], v[80:81]
	v_pk_mul_f32 v[8:9], v[8:9], v[84:85]
	v_pk_mul_f32 v[4:5], v[4:5], v[88:89]
	v_pk_mul_f32 v[14:15], v[14:15], v[82:83]
	v_pk_mul_f32 v[10:11], v[10:11], v[86:87]
	v_pk_mul_f32 v[6:7], v[6:7], v[90:91]
	v_pk_mul_f32 v[2:3], v[2:3], v[94:95]
	v_pk_mul_f32 v[0:1], v[0:1], v[92:93]
.LBB0_700:
	s_add_u32 s48, s68, 0x20000
	s_addc_u32 s49, s69, 0
	s_lshl_b32 s45, s38, 13
	s_add_i32 s45, s45, s39
	s_waitcnt vmcnt(0) lgkmcnt(0)
	s_barrier
	v_add_u32_e32 v185, s43, v184
	ds_read_b128 v[80:83], v185 offset:49152
	ds_read_b128 v[190:193], v185 offset:49664
	s_cmp_lt_i32 s18, 4
	s_cbranch_scc1 .Lattn_nodma_Lattn_m0_res2
	s_mov_b32 m0, s45
	v_lshl_add_u64 v[212:213], v[172:173], 0, s[8:9]
	global_load_lds_dwordx4 v[212:213], off
	s_add_i32 s98, s45, 0xfffff000
	s_mov_b32 m0, s98
	s_mov_b32 s100, 0xffffffc0
	s_mov_b32 s101, -1
	v_lshl_add_u64 v[214:215], v[212:213], 0, s[100:101]
	global_load_lds_dwordx4 v[214:215], off
	s_add_i32 s99, s44, s24
	s_mov_b32 m0, s99
	v_lshl_add_u64 v[212:213], s[48:49], 0, v[166:167]
	global_load_lds_dwordx4 v[212:213], off
	s_add_u32 s100, s48, 0xffff8000
	s_addc_u32 s101, s49, -1
	s_addk_i32 s99, 0xf000
	s_mov_b32 m0, s99
	v_lshl_add_u64 v[214:215], s[100:101], 0, v[166:167]
	global_load_lds_dwordx4 v[214:215], off
	s_add_i32 s98, s44, s25
	s_mov_b32 m0, s98
	v_lshl_add_u64 v[212:213], s[48:49], 0, v[170:171]
	global_load_lds_dwordx4 v[212:213], off
	s_addk_i32 s98, 0xf000
	s_mov_b32 m0, s98
	v_lshl_add_u64 v[214:215], s[100:101], 0, v[170:171]
	global_load_lds_dwordx4 v[214:215], off
.Lattn_nodma_Lattn_m0_res2:
	s_add_i32 s44, s44, s25
	s_waitcnt lgkmcnt(1)
	v_mfma_f32_32x32x16_bf16 v[96:111], v[80:83], v[156:159], v[64:79]
	ds_read_b128 v[194:197], v185 offset:51200
	ds_read_b128 v[198:201], v185 offset:51712
	v_add_f32_e32 v84, v130, v128
	v_add_f32_e32 v85, v131, v129
	v_cvt_pk_bf16_f32 v128, v128, v129
	v_cvt_pk_bf16_f32 v129, v130, v131
	v_cvt_pk_bf16_f32 v130, v132, v133
	v_cvt_pk_bf16_f32 v131, v134, v135
	v_add_f32_e32 v80, v132, v84
	v_add_f32_e32 v81, v133, v85
	v_add_f32_e32 v132, v134, v80
	v_add_f32_e32 v133, v135, v81
	s_waitcnt lgkmcnt(2)
	v_mfma_f32_32x32x16_bf16 v[80:95], v[190:193], v[156:159], v[64:79]
	s_waitcnt lgkmcnt(1)
	v_mfma_f32_32x32x16_bf16 v[96:111], v[194:197], v[152:155], v[96:111]
	ds_read_b128 v[190:193], v185 offset:53248
	ds_read_b128 v[202:205], v185 offset:53760
	v_add_f32_e32 v132, v136, v132
	v_add_f32_e32 v133, v137, v133
	v_add_f32_e32 v189, v138, v132
	v_add_f32_e32 v206, v139, v133
	v_cvt_pk_bf16_f32 v132, v136, v137
	v_cvt_pk_bf16_f32 v133, v138, v139
	v_cvt_pk_bf16_f32 v134, v140, v141
	v_cvt_pk_bf16_f32 v135, v142, v143
	s_waitcnt lgkmcnt(2)
	v_mfma_f32_32x32x16_bf16 v[80:95], v[198:201], v[152:155], v[80:95]
	v_add_f32_e32 v136, v140, v189
	v_add_f32_e32 v137, v141, v206
	v_add_f32_e32 v189, v142, v136
	v_add_f32_e32 v194, v143, v137
	s_waitcnt lgkmcnt(1)
	v_mfma_f32_32x32x16_bf16 v[96:111], v[190:193], v[148:151], v[96:111]
	ds_read_b128 v[136:139], v185 offset:55296
	ds_read_b128 v[140:143], v185 offset:55808
	v_add_f32_e32 v185, v112, v189
	v_add_f32_e32 v189, v113, v194
	v_add_f32_e32 v185, v114, v185
	v_add_f32_e32 v189, v115, v189
	v_cvt_pk_bf16_f32 v112, v112, v113
	v_cvt_pk_bf16_f32 v113, v114, v115
	v_cvt_pk_bf16_f32 v114, v116, v117
	v_cvt_pk_bf16_f32 v115, v118, v119
	s_waitcnt lgkmcnt(2)
	v_mfma_f32_32x32x16_bf16 v[80:95], v[202:205], v[148:151], v[80:95]
	v_lshl_add_u32 v206, s42, 14, v183
	ds_read_b64_tr_b16 v[198:199], v206 offset:0
	ds_read_b64_tr_b16 v[200:201], v206 offset:0x800
	ds_read_b64_tr_b16 v[190:191], v206 offset:0x1000
	ds_read_b64_tr_b16 v[192:193], v206 offset:0x1800
	ds_read_b64_tr_b16 v[212:213], v206 offset:0x2000
	ds_read_b64_tr_b16 v[214:215], v206 offset:0x2800
	v_add_f32_e32 v116, v116, v185
	v_add_f32_e32 v117, v117, v189
	v_add_f32_e32 v116, v118, v116
	v_add_f32_e32 v117, v119, v117
	s_waitcnt lgkmcnt(7)
	v_mfma_f32_32x32x16_bf16 v[96:111], v[136:139], v[144:147], v[96:111]
	ds_read_b64_tr_b16 v[202:203], v206 offset:0x3000
	ds_read_b64_tr_b16 v[204:205], v206 offset:0x3800
	ds_read_b64_tr_b16 v[216:217], v206 offset:0x200
	ds_read_b64_tr_b16 v[218:219], v206 offset:0xa00
	v_add_f32_e32 v116, v120, v116
	v_add_f32_e32 v117, v121, v117
	v_add_f32_e32 v185, v122, v116
	v_add_f32_e32 v189, v123, v117
	v_cvt_pk_bf16_f32 v116, v120, v121
	v_cvt_pk_bf16_f32 v117, v122, v123
	v_cvt_pk_bf16_f32 v118, v124, v125
	v_cvt_pk_bf16_f32 v119, v126, v127
	s_waitcnt lgkmcnt(10)
	v_mfma_f32_32x32x16_bf16 v[80:95], v[140:143], v[144:147], v[80:95]
	v_add_f32_e32 v120, v124, v185
	v_add_f32_e32 v121, v125, v189
	v_add_f32_e32 v120, v126, v120
	v_add_f32_e32 v121, v127, v121
	ds_read_b64_tr_b16 v[220:221], v206 offset:0x1200
	ds_read_b64_tr_b16 v[222:223], v206 offset:0x1a00
	ds_read_b64_tr_b16 v[224:225], v206 offset:0x2200
	ds_read_b64_tr_b16 v[226:227], v206 offset:0x2a00
	s_waitcnt lgkmcnt(12)
	v_mfma_f32_32x32x16_bf16 v[48:63], v[128:131], v[198:201], v[48:63]
	v_max_f32_e32 v122, v96, v97
	v_max3_f32 v123, v99, v100, v101
	v_max3_f32 v122, v122, v98, v102
	v_max3_f32 v123, v123, v104, v105
	ds_read_b64_tr_b16 v[198:199], v206 offset:0x3200
	ds_read_b64_tr_b16 v[200:201], v206 offset:0x3a00
	s_waitcnt lgkmcnt(12)
	v_mfma_f32_32x32x16_bf16 v[48:63], v[132:135], v[190:193], v[48:63]
	v_max3_f32 v122, v122, v103, v106
	v_max3_f32 v123, v123, v108, v109
	v_max3_f32 v122, v122, v107, v110
	v_max3_f32 v122, v122, v111, v123
	v_add_f32_e32 v120, v120, v121
	v_mov_b32_e32 v121, v120
	ds_read_b64_tr_b16 v[190:191], v206 offset:0x400
	ds_read_b64_tr_b16 v[192:193], v206 offset:0xc00
	s_waitcnt lgkmcnt(12)
	v_mfma_f32_32x32x16_bf16 v[48:63], v[112:115], v[212:215], v[48:63]
	v_max3_f32 v123, v80, v81, v82
	v_max3_f32 v124, v83, v84, v85
	v_max3_f32 v123, v123, v86, v87
	v_max3_f32 v124, v124, v88, v89
	v_permlane32_swap_b32_e32 v120, v121
	v_max3_f32 v123, v123, v90, v91
	ds_read_b64_tr_b16 v[212:213], v206 offset:0x1400
	ds_read_b64_tr_b16 v[214:215], v206 offset:0x1c00
	s_waitcnt lgkmcnt(12)
	v_mfma_f32_32x32x16_bf16 v[48:63], v[116:119], v[202:205], v[48:63]
	v_max3_f32 v124, v124, v92, v93
	v_max3_f32 v123, v123, v94, v95
	v_max3_f32 v122, v122, v123, v124
	v_mov_b32_e32 v123, v122
	ds_read_b64_tr_b16 v[202:203], v206 offset:0x2400
	ds_read_b64_tr_b16 v[204:205], v206 offset:0x2c00
	s_waitcnt lgkmcnt(12)
	v_mfma_f32_32x32x16_bf16 v[32:47], v[128:131], v[216:219], v[32:47]
	v_permlane32_swap_b32_e32 v122, v123
	v_max_f32_e32 v122, v122, v123
	v_cmp_lt_f32_e32 vcc, s47, v122
	v_mov_b32_e32 v185, 1.0
	s_cbranch_vccnz .LBB0_708
.Lattn_m0_res2:
	ds_read_b64_tr_b16 v[216:217], v206 offset:0x3400
	ds_read_b64_tr_b16 v[218:219], v206 offset:0x3c00
	s_waitcnt lgkmcnt(12)
	v_mfma_f32_32x32x16_bf16 v[32:47], v[132:135], v[220:223], v[32:47]
	v_exp_f32_e32 v96, v96
	v_exp_f32_e32 v97, v97
	v_exp_f32_e32 v98, v98
	ds_read_b64_tr_b16 v[220:221], v206 offset:0x600
	ds_read_b64_tr_b16 v[222:223], v206 offset:0xe00
	s_waitcnt lgkmcnt(12)
	v_mfma_f32_32x32x16_bf16 v[32:47], v[112:115], v[224:227], v[32:47]
	v_exp_f32_e32 v99, v99
	v_exp_f32_e32 v100, v100
	v_exp_f32_e32 v101, v101
	ds_read_b64_tr_b16 v[224:225], v206 offset:0x1600
	ds_read_b64_tr_b16 v[226:227], v206 offset:0x1e00
	s_waitcnt lgkmcnt(12)
	v_mfma_f32_32x32x16_bf16 v[32:47], v[116:119], v[198:201], v[32:47]
	v_exp_f32_e32 v102, v102
	v_exp_f32_e32 v103, v103
	v_exp_f32_e32 v104, v104
	ds_read_b64_tr_b16 v[198:199], v206 offset:0x2600
	ds_read_b64_tr_b16 v[200:201], v206 offset:0x2e00
	s_waitcnt lgkmcnt(12)
	v_mfma_f32_32x32x16_bf16 v[16:31], v[128:131], v[190:193], v[16:31]
	v_exp_f32_e32 v105, v105
	v_exp_f32_e32 v106, v106
	v_exp_f32_e32 v107, v107
	ds_read_b64_tr_b16 v[190:191], v206 offset:0x3600
	ds_read_b64_tr_b16 v[192:193], v206 offset:0x3e00
	s_waitcnt lgkmcnt(12)
	v_mfma_f32_32x32x16_bf16 v[16:31], v[132:135], v[212:215], v[16:31]
	v_exp_f32_e32 v108, v108
	v_exp_f32_e32 v109, v109
	v_exp_f32_e32 v110, v110
	s_waitcnt lgkmcnt(10)
	v_mfma_f32_32x32x16_bf16 v[16:31], v[112:115], v[202:205], v[16:31]
	v_exp_f32_e32 v111, v111
	v_exp_f32_e32 v80, v80
	v_exp_f32_e32 v81, v81
	s_waitcnt lgkmcnt(8)
	v_mfma_f32_32x32x16_bf16 v[16:31], v[116:119], v[216:219], v[16:31]
	v_exp_f32_e32 v82, v82
	v_exp_f32_e32 v83, v83
	v_exp_f32_e32 v84, v84
	s_waitcnt lgkmcnt(6)
	v_mfma_f32_32x32x16_bf16 v[0:15], v[128:131], v[220:223], v[0:15]
	v_exp_f32_e32 v85, v85
	v_exp_f32_e32 v86, v86
	v_exp_f32_e32 v87, v87
	s_waitcnt lgkmcnt(4)
	v_mfma_f32_32x32x16_bf16 v[0:15], v[132:135], v[224:227], v[0:15]
	v_exp_f32_e32 v88, v88
	v_exp_f32_e32 v89, v89
	v_exp_f32_e32 v90, v90
	s_waitcnt lgkmcnt(2)
	v_mfma_f32_32x32x16_bf16 v[0:15], v[112:115], v[198:201], v[0:15]
	v_exp_f32_e32 v91, v91
	v_exp_f32_e32 v92, v92
	v_exp_f32_e32 v93, v93
	s_waitcnt lgkmcnt(0)
	v_mfma_f32_32x32x16_bf16 v[0:15], v[116:119], v[190:193], v[0:15]
	v_exp_f32_e32 v94, v94
	v_exp_f32_e32 v95, v95
	v_cmp_gt_f32_e32 vcc, 1.0, v185
	s_cbranch_vccz .LBB0_705
	s_and_saveexec_b64 s[70:71], s[0:1]
	ds_write_b32 v177, v185 offset:128
	s_or_b64 exec, exec, s[70:71]
	s_waitcnt lgkmcnt(0)
	v_add_u32_e32 v126, s19, v168
	ds_read_b128 v[112:115], v126 offset:224
	ds_read_b128 v[116:119], v126 offset:192
	ds_read_b128 v[122:125], v126 offset:160
	ds_read_b128 v[126:129], v126 offset:128
	s_waitcnt lgkmcnt(3)
	v_pk_mul_f32 v[60:61], v[60:61], v[112:113]
	s_waitcnt lgkmcnt(2)
	v_pk_mul_f32 v[56:57], v[56:57], v[116:117]
	s_waitcnt lgkmcnt(1)
	v_pk_mul_f32 v[52:53], v[52:53], v[122:123]
	v_pk_mul_f32 v[62:63], v[62:63], v[114:115]
	v_pk_mul_f32 v[58:59], v[58:59], v[118:119]
	v_pk_mul_f32 v[54:55], v[54:55], v[124:125]
	s_waitcnt lgkmcnt(0)
	v_pk_mul_f32 v[50:51], v[50:51], v[128:129]
	v_pk_mul_f32 v[48:49], v[48:49], v[126:127]
	v_pk_mul_f32 v[44:45], v[44:45], v[112:113]
	v_pk_mul_f32 v[40:41], v[40:41], v[116:117]
	v_pk_mul_f32 v[36:37], v[36:37], v[122:123]
	v_pk_mul_f32 v[46:47], v[46:47], v[114:115]
	v_pk_mul_f32 v[42:43], v[42:43], v[118:119]
	v_pk_mul_f32 v[38:39], v[38:39], v[124:125]
	v_pk_mul_f32 v[34:35], v[34:35], v[128:129]
	v_pk_mul_f32 v[32:33], v[32:33], v[126:127]
	v_pk_mul_f32 v[28:29], v[28:29], v[112:113]
	v_pk_mul_f32 v[24:25], v[24:25], v[116:117]
	v_pk_mul_f32 v[20:21], v[20:21], v[122:123]
	v_pk_mul_f32 v[30:31], v[30:31], v[114:115]
	v_pk_mul_f32 v[26:27], v[26:27], v[118:119]
	v_pk_mul_f32 v[22:23], v[22:23], v[124:125]
	v_pk_mul_f32 v[18:19], v[18:19], v[128:129]
	v_pk_mul_f32 v[16:17], v[16:17], v[126:127]
	v_pk_mul_f32 v[12:13], v[12:13], v[112:113]
	v_pk_mul_f32 v[8:9], v[8:9], v[116:117]
	v_pk_mul_f32 v[4:5], v[4:5], v[122:123]
	v_pk_mul_f32 v[14:15], v[14:15], v[114:115]
	v_pk_mul_f32 v[10:11], v[10:11], v[118:119]
	v_pk_mul_f32 v[6:7], v[6:7], v[124:125]
	v_pk_mul_f32 v[2:3], v[2:3], v[128:129]
	v_pk_mul_f32 v[0:1], v[0:1], v[126:127]

;     ...
;     f32x16 pA0, pA1, pB0, pB1; float alA, alB; bf16x8 pa0, pa1, pa2, pa3;
;     int sp = 0, sc_ = 1, sn = 2;
.LBB0_720:
	s_lshl_b32 s43, s34, 13
	s_mov_b32 s42, s38
	v_lshl_add_u32 v187, s42, 13, v186
	ds_read_b128 v[112:115], v187 offset:49152
	ds_read_b128 v[188:191], v187 offset:49664
	s_mov_b32 s38, s44
	s_cmp_lt_i32 s18, 4
	s_cbranch_scc1 .Lattn_nodma_Lattn_m1_res1
	s_add_i32 s98, s43, s39
	s_mov_b32 m0, s98
	s_mov_b32 s100, 0xffffffc0
	s_mov_b32 s101, -1
	global_load_lds_dwordx4 v[172:173], off
	s_addk_i32 s98, 0xf000
	s_mov_b32 m0, s98
	v_lshl_add_u64 v[212:213], v[172:173], 0, s[100:101]
	global_load_lds_dwordx4 v[212:213], off
	s_lshl_b32 s98, s34, 14
	s_add_i32 s99, s98, s24
	s_mov_b32 m0, s99
	v_lshl_add_u64 v[212:213], s[4:5], 0, v[166:167]
	global_load_lds_dwordx4 v[212:213], off
	s_add_u32 s100, s4, 0xffff8000
	s_addc_u32 s101, s5, -1
	s_addk_i32 s99, 0xf000
	s_mov_b32 m0, s99
	v_lshl_add_u64 v[214:215], s[100:101], 0, v[166:167]
	global_load_lds_dwordx4 v[214:215], off
	s_add_i32 s98, s98, s25
	s_mov_b32 m0, s98
	v_lshl_add_u64 v[212:213], s[4:5], 0, v[170:171]
	global_load_lds_dwordx4 v[212:213], off
	s_addk_i32 s98, 0xf000
	s_mov_b32 m0, s98
	v_lshl_add_u64 v[214:215], s[100:101], 0, v[170:171]
	global_load_lds_dwordx4 v[214:215], off
.Lattn_nodma_Lattn_m1_res1:
	s_waitcnt lgkmcnt(1)
	v_mfma_f32_32x32x16_bf16 v[128:143], v[112:115], v[156:159], v[64:79]
	ds_read_b128 v[192:195], v187 offset:51200
	ds_read_b128 v[196:199], v187 offset:51712
	v_add_f32_e32 v116, v98, v96
	v_add_f32_e32 v117, v99, v97
	v_cvt_pk_bf16_f32 v96, v96, v97
	v_cvt_pk_bf16_f32 v97, v98, v99
	v_cvt_pk_bf16_f32 v98, v100, v101
	v_cvt_pk_bf16_f32 v99, v102, v103
	v_add_f32_e32 v100, v100, v116
	v_add_f32_e32 v101, v101, v117
	s_waitcnt lgkmcnt(2)
	v_mfma_f32_32x32x16_bf16 v[112:127], v[188:191], v[156:159], v[64:79]
	v_add_f32_e32 v100, v102, v100
	v_add_f32_e32 v101, v103, v101
	s_waitcnt lgkmcnt(1)
	v_mfma_f32_32x32x16_bf16 v[128:143], v[192:195], v[152:155], v[128:143]
	ds_read_b128 v[188:191], v187 offset:53248
	ds_read_b128 v[200:203], v187 offset:53760
	v_add_f32_e32 v100, v104, v100
	v_add_f32_e32 v101, v105, v101
	v_add_f32_e32 v204, v106, v100
	v_add_f32_e32 v205, v107, v101
	v_cvt_pk_bf16_f32 v100, v104, v105
	v_cvt_pk_bf16_f32 v101, v106, v107
	v_cvt_pk_bf16_f32 v102, v108, v109
	v_cvt_pk_bf16_f32 v103, v110, v111
	s_waitcnt lgkmcnt(2)
	v_mfma_f32_32x32x16_bf16 v[112:127], v[196:199], v[152:155], v[112:127]
	v_add_f32_e32 v104, v108, v204
	v_add_f32_e32 v105, v109, v205
	v_add_f32_e32 v192, v110, v104
	v_add_f32_e32 v193, v111, v105
	s_waitcnt lgkmcnt(1)
	v_mfma_f32_32x32x16_bf16 v[128:143], v[188:191], v[148:151], v[128:143]
	ds_read_b128 v[104:107], v187 offset:55296
	ds_read_b128 v[108:111], v187 offset:55808
	v_add_f32_e32 v187, v80, v192
	v_add_f32_e32 v192, v81, v193
	v_add_f32_e32 v187, v82, v187
	v_add_f32_e32 v192, v83, v192
	v_cvt_pk_bf16_f32 v80, v80, v81
	v_cvt_pk_bf16_f32 v81, v82, v83
	v_cvt_pk_bf16_f32 v82, v84, v85
	v_cvt_pk_bf16_f32 v83, v86, v87
	s_waitcnt lgkmcnt(2)
	v_mfma_f32_32x32x16_bf16 v[112:127], v[200:203], v[148:151], v[112:127]
	s_lshl_b32 s44, s38, 14
	v_add_u32_e32 v191, s44, v185
	ds_read_b64_tr_b16 v[196:197], v191 offset:0
	ds_read_b64_tr_b16 v[198:199], v191 offset:0x800
	ds_read_b64_tr_b16 v[212:213], v191 offset:0x1000
	ds_read_b64_tr_b16 v[214:215], v191 offset:0x1800
	ds_read_b64_tr_b16 v[216:217], v191 offset:0x2000
	ds_read_b64_tr_b16 v[218:219], v191 offset:0x2800
	v_add_f32_e32 v84, v84, v187
	v_add_f32_e32 v85, v85, v192
	v_add_f32_e32 v84, v86, v84
	v_add_f32_e32 v85, v87, v85
	s_waitcnt lgkmcnt(7)
	v_mfma_f32_32x32x16_bf16 v[128:143], v[104:107], v[144:147], v[128:143]
	ds_read_b64_tr_b16 v[200:201], v191 offset:0x3000
	ds_read_b64_tr_b16 v[202:203], v191 offset:0x3800
	ds_read_b64_tr_b16 v[192:193], v191 offset:0x200
	ds_read_b64_tr_b16 v[194:195], v191 offset:0xa00
	v_add_f32_e32 v84, v88, v84
	v_add_f32_e32 v85, v89, v85
	v_add_f32_e32 v187, v90, v84
	v_add_f32_e32 v188, v91, v85
	v_cvt_pk_bf16_f32 v84, v88, v89
	v_cvt_pk_bf16_f32 v85, v90, v91
	v_cvt_pk_bf16_f32 v86, v92, v93
	v_cvt_pk_bf16_f32 v87, v94, v95
	s_waitcnt lgkmcnt(10)
	v_mfma_f32_32x32x16_bf16 v[112:127], v[108:111], v[144:147], v[112:127]
	v_add_f32_e32 v88, v92, v187
	v_add_f32_e32 v89, v93, v188
	v_add_f32_e32 v88, v94, v88
	v_add_f32_e32 v89, v95, v89
	ds_read_b64_tr_b16 v[220:221], v191 offset:0x1200
	ds_read_b64_tr_b16 v[222:223], v191 offset:0x1a00
	ds_read_b64_tr_b16 v[224:225], v191 offset:0x2200
	ds_read_b64_tr_b16 v[226:227], v191 offset:0x2a00
	s_waitcnt lgkmcnt(12)
	v_mfma_f32_32x32x16_bf16 v[48:63], v[96:99], v[196:199], v[48:63]
	v_max_f32_e32 v90, v128, v129
	v_max3_f32 v91, v131, v132, v133
	v_max3_f32 v90, v90, v130, v134
	v_max3_f32 v91, v91, v136, v137
	ds_read_b64_tr_b16 v[196:197], v191 offset:0x3200
	ds_read_b64_tr_b16 v[198:199], v191 offset:0x3a00
	s_waitcnt lgkmcnt(12)
	v_mfma_f32_32x32x16_bf16 v[48:63], v[100:103], v[212:215], v[48:63]
	v_max3_f32 v90, v90, v135, v138
	v_max3_f32 v91, v91, v140, v141
	v_max3_f32 v90, v90, v139, v142
	v_max3_f32 v90, v90, v143, v91
	v_add_f32_e32 v188, v88, v89
	v_mov_b32_e32 v189, v188
	ds_read_b64_tr_b16 v[212:213], v191 offset:0x400
	ds_read_b64_tr_b16 v[214:215], v191 offset:0xc00
	s_waitcnt lgkmcnt(12)
	v_mfma_f32_32x32x16_bf16 v[48:63], v[80:83], v[216:219], v[48:63]
	v_max3_f32 v88, v112, v113, v114
	v_max3_f32 v89, v115, v116, v117
	v_max3_f32 v88, v88, v118, v119
	v_max3_f32 v89, v89, v120, v121
	v_permlane32_swap_b32_e32 v188, v189
	v_max3_f32 v88, v88, v122, v123
	ds_read_b64_tr_b16 v[216:217], v191 offset:0x1400
	ds_read_b64_tr_b16 v[218:219], v191 offset:0x1c00
	s_waitcnt lgkmcnt(12)
	v_mfma_f32_32x32x16_bf16 v[48:63], v[84:87], v[200:203], v[48:63]
	v_max3_f32 v89, v89, v124, v125
	v_max3_f32 v88, v88, v126, v127
	v_max3_f32 v88, v90, v88, v89
	v_mov_b32_e32 v89, v88
	ds_read_b64_tr_b16 v[200:201], v191 offset:0x2400
	ds_read_b64_tr_b16 v[202:203], v191 offset:0x2c00
	s_waitcnt lgkmcnt(12)
	v_mfma_f32_32x32x16_bf16 v[32:47], v[96:99], v[192:195], v[32:47]
	v_permlane32_swap_b32_e32 v88, v89
	v_max_f32_e32 v88, v88, v89
	v_cmp_lt_f32_e32 vcc, s47, v88
	v_mov_b32_e32 v190, 1.0
	s_cbranch_vccnz .LBB0_732
;     ...
;     f32x16 pA0, pA1, pB0, pB1; float alA, alB; bf16x8 pa0, pa1, pa2, pa3;
;     int sp = 0, sc_ = 1, sn = 2;
.Lattn_m1_res1:
	ds_read_b64_tr_b16 v[192:193], v191 offset:0x3400
	ds_read_b64_tr_b16 v[194:195], v191 offset:0x3c00
	s_waitcnt lgkmcnt(12)
	v_mfma_f32_32x32x16_bf16 v[32:47], v[100:103], v[220:223], v[32:47]
	v_exp_f32_e32 v128, v128
	v_exp_f32_e32 v129, v129
	v_exp_f32_e32 v130, v130
	ds_read_b64_tr_b16 v[220:221], v191 offset:0x600
	ds_read_b64_tr_b16 v[222:223], v191 offset:0xe00
	s_waitcnt lgkmcnt(12)
	v_mfma_f32_32x32x16_bf16 v[32:47], v[80:83], v[224:227], v[32:47]
	v_exp_f32_e32 v131, v131
	v_exp_f32_e32 v132, v132
	v_exp_f32_e32 v133, v133
	ds_read_b64_tr_b16 v[224:225], v191 offset:0x1600
	ds_read_b64_tr_b16 v[226:227], v191 offset:0x1e00
	s_waitcnt lgkmcnt(12)
	v_mfma_f32_32x32x16_bf16 v[32:47], v[84:87], v[196:199], v[32:47]
	v_exp_f32_e32 v134, v134
	v_exp_f32_e32 v135, v135
	v_exp_f32_e32 v136, v136
	ds_read_b64_tr_b16 v[196:197], v191 offset:0x2600
	ds_read_b64_tr_b16 v[198:199], v191 offset:0x2e00
	s_waitcnt lgkmcnt(12)
	v_mfma_f32_32x32x16_bf16 v[16:31], v[96:99], v[212:215], v[16:31]
	v_exp_f32_e32 v137, v137
	v_exp_f32_e32 v138, v138
	v_exp_f32_e32 v139, v139
	ds_read_b64_tr_b16 v[212:213], v191 offset:0x3600
	ds_read_b64_tr_b16 v[214:215], v191 offset:0x3e00
	s_waitcnt lgkmcnt(12)
	v_mfma_f32_32x32x16_bf16 v[16:31], v[100:103], v[216:219], v[16:31]
	v_exp_f32_e32 v140, v140
	v_exp_f32_e32 v141, v141
	v_exp_f32_e32 v142, v142
	s_waitcnt lgkmcnt(10)
	v_mfma_f32_32x32x16_bf16 v[16:31], v[80:83], v[200:203], v[16:31]
	v_exp_f32_e32 v143, v143
	v_exp_f32_e32 v112, v112
	v_exp_f32_e32 v113, v113
	s_waitcnt lgkmcnt(8)
	v_mfma_f32_32x32x16_bf16 v[16:31], v[84:87], v[192:195], v[16:31]
	v_exp_f32_e32 v114, v114
	v_exp_f32_e32 v115, v115
	v_exp_f32_e32 v116, v116
	s_waitcnt lgkmcnt(6)
	v_mfma_f32_32x32x16_bf16 v[0:15], v[96:99], v[220:223], v[0:15]
	v_exp_f32_e32 v117, v117
	v_exp_f32_e32 v118, v118
	v_exp_f32_e32 v119, v119
	s_waitcnt lgkmcnt(4)
	v_mfma_f32_32x32x16_bf16 v[0:15], v[100:103], v[224:227], v[0:15]
	v_exp_f32_e32 v120, v120
	v_exp_f32_e32 v121, v121
	v_exp_f32_e32 v122, v122
	s_waitcnt lgkmcnt(2)
	v_mfma_f32_32x32x16_bf16 v[0:15], v[80:83], v[196:199], v[0:15]
	v_exp_f32_e32 v123, v123
	v_exp_f32_e32 v124, v124
	v_exp_f32_e32 v125, v125
	s_waitcnt lgkmcnt(0)
	v_mfma_f32_32x32x16_bf16 v[0:15], v[84:87], v[212:215], v[0:15]
	v_exp_f32_e32 v126, v126
	v_exp_f32_e32 v127, v127
	v_cmp_gt_f32_e32 vcc, 1.0, v190
	s_cbranch_vccz .LBB0_725
	s_and_saveexec_b64 s[52:53], s[0:1]
	ds_write_b32 v180, v190 offset:128
	s_or_b64 exec, exec, s[52:53]
	s_waitcnt lgkmcnt(0)
	v_add_u32_e32 v92, s19, v168
	ds_read_b128 v[80:83], v92 offset:224
	ds_read_b128 v[84:87], v92 offset:192
	ds_read_b128 v[88:91], v92 offset:160
	ds_read_b128 v[92:95], v92 offset:128
	s_waitcnt lgkmcnt(3)
	v_pk_mul_f32 v[60:61], v[60:61], v[80:81]
	s_waitcnt lgkmcnt(2)
	v_pk_mul_f32 v[56:57], v[56:57], v[84:85]
	s_waitcnt lgkmcnt(1)
	v_pk_mul_f32 v[52:53], v[52:53], v[88:89]
	v_pk_mul_f32 v[62:63], v[62:63], v[82:83]
	v_pk_mul_f32 v[58:59], v[58:59], v[86:87]
	v_pk_mul_f32 v[54:55], v[54:55], v[90:91]
	s_waitcnt lgkmcnt(0)
	v_pk_mul_f32 v[50:51], v[50:51], v[94:95]
	v_pk_mul_f32 v[48:49], v[48:49], v[92:93]
	v_pk_mul_f32 v[44:45], v[44:45], v[80:81]
	v_pk_mul_f32 v[40:41], v[40:41], v[84:85]
	v_pk_mul_f32 v[36:37], v[36:37], v[88:89]
	v_pk_mul_f32 v[46:47], v[46:47], v[82:83]
	v_pk_mul_f32 v[42:43], v[42:43], v[86:87]
	v_pk_mul_f32 v[38:39], v[38:39], v[90:91]
	v_pk_mul_f32 v[34:35], v[34:35], v[94:95]
	v_pk_mul_f32 v[32:33], v[32:33], v[92:93]
	v_pk_mul_f32 v[28:29], v[28:29], v[80:81]
	v_pk_mul_f32 v[24:25], v[24:25], v[84:85]
	v_pk_mul_f32 v[20:21], v[20:21], v[88:89]
	v_pk_mul_f32 v[30:31], v[30:31], v[82:83]
	v_pk_mul_f32 v[26:27], v[26:27], v[86:87]
	v_pk_mul_f32 v[22:23], v[22:23], v[90:91]
	v_pk_mul_f32 v[18:19], v[18:19], v[94:95]
	v_pk_mul_f32 v[16:17], v[16:17], v[92:93]
	v_pk_mul_f32 v[12:13], v[12:13], v[80:81]
	v_pk_mul_f32 v[8:9], v[8:9], v[84:85]
	v_pk_mul_f32 v[4:5], v[4:5], v[88:89]
	v_pk_mul_f32 v[14:15], v[14:15], v[82:83]
	v_pk_mul_f32 v[10:11], v[10:11], v[86:87]
	v_pk_mul_f32 v[6:7], v[6:7], v[90:91]
	v_pk_mul_f32 v[2:3], v[2:3], v[94:95]
	v_pk_mul_f32 v[0:1], v[0:1], v[92:93]
.LBB0_725:
	s_add_u32 s48, s4, 0x20000
	s_addc_u32 s49, s5, 0
	s_lshl_b32 s45, s38, 13
	s_add_i32 s45, s45, s39
	s_waitcnt vmcnt(0) lgkmcnt(0)
	s_barrier
	v_add_u32_e32 v187, s43, v186
	ds_read_b128 v[80:83], v187 offset:49152
	ds_read_b128 v[192:195], v187 offset:49664
	s_cmp_lt_i32 s18, 4
	s_cbranch_scc1 .Lattn_nodma_Lattn_m1_res2
	s_mov_b32 m0, s45
	v_lshl_add_u64 v[212:213], v[172:173], 0, s[8:9]
	global_load_lds_dwordx4 v[212:213], off
	s_add_i32 s98, s45, 0xfffff000
	s_mov_b32 m0, s98
	s_mov_b32 s100, 0xffffffc0
	s_mov_b32 s101, -1
	v_lshl_add_u64 v[214:215], v[212:213], 0, s[100:101]
	global_load_lds_dwordx4 v[214:215], off
	s_add_i32 s99, s44, s24
	s_mov_b32 m0, s99
	v_lshl_add_u64 v[212:213], s[48:49], 0, v[166:167]
	global_load_lds_dwordx4 v[212:213], off
	s_add_u32 s100, s48, 0xffff8000
	s_addc_u32 s101, s49, -1
	s_addk_i32 s99, 0xf000
	s_mov_b32 m0, s99
	v_lshl_add_u64 v[214:215], s[100:101], 0, v[166:167]
	global_load_lds_dwordx4 v[214:215], off
	s_add_i32 s98, s44, s25
	s_mov_b32 m0, s98
	v_lshl_add_u64 v[212:213], s[48:49], 0, v[170:171]
	global_load_lds_dwordx4 v[212:213], off
	s_addk_i32 s98, 0xf000
	s_mov_b32 m0, s98
	v_lshl_add_u64 v[214:215], s[100:101], 0, v[170:171]
	global_load_lds_dwordx4 v[214:215], off
.Lattn_nodma_Lattn_m1_res2:
	s_add_i32 s44, s44, s25
	s_waitcnt lgkmcnt(1)
	v_mfma_f32_32x32x16_bf16 v[96:111], v[80:83], v[156:159], v[64:79]
	ds_read_b128 v[196:199], v187 offset:51200
	ds_read_b128 v[200:203], v187 offset:51712
	v_add_f32_e32 v84, v130, v128
	v_add_f32_e32 v85, v131, v129
	v_cvt_pk_bf16_f32 v128, v128, v129
	v_cvt_pk_bf16_f32 v129, v130, v131
	v_cvt_pk_bf16_f32 v130, v132, v133
	v_cvt_pk_bf16_f32 v131, v134, v135
	v_add_f32_e32 v80, v132, v84
	v_add_f32_e32 v81, v133, v85
	v_add_f32_e32 v132, v134, v80
	v_add_f32_e32 v133, v135, v81
	s_waitcnt lgkmcnt(2)
	v_mfma_f32_32x32x16_bf16 v[80:95], v[192:195], v[156:159], v[64:79]
	s_waitcnt lgkmcnt(1)
	v_mfma_f32_32x32x16_bf16 v[96:111], v[196:199], v[152:155], v[96:111]
	ds_read_b128 v[192:195], v187 offset:53248
	ds_read_b128 v[204:207], v187 offset:53760
	v_add_f32_e32 v132, v136, v132
	v_add_f32_e32 v133, v137, v133
	v_add_f32_e32 v191, v138, v132
	v_add_f32_e32 v208, v139, v133
	v_cvt_pk_bf16_f32 v132, v136, v137
	v_cvt_pk_bf16_f32 v133, v138, v139
	v_cvt_pk_bf16_f32 v134, v140, v141
	v_cvt_pk_bf16_f32 v135, v142, v143
	s_waitcnt lgkmcnt(2)
	v_mfma_f32_32x32x16_bf16 v[80:95], v[200:203], v[152:155], v[80:95]
	v_add_f32_e32 v136, v140, v191
	v_add_f32_e32 v137, v141, v208
	v_add_f32_e32 v191, v142, v136
	v_add_f32_e32 v196, v143, v137
	s_waitcnt lgkmcnt(1)
	v_mfma_f32_32x32x16_bf16 v[96:111], v[192:195], v[148:151], v[96:111]
	ds_read_b128 v[136:139], v187 offset:55296
	ds_read_b128 v[140:143], v187 offset:55808
	v_add_f32_e32 v187, v112, v191
	v_add_f32_e32 v191, v113, v196
	v_add_f32_e32 v187, v114, v187
	v_add_f32_e32 v191, v115, v191
	v_cvt_pk_bf16_f32 v112, v112, v113
	v_cvt_pk_bf16_f32 v113, v114, v115
	v_cvt_pk_bf16_f32 v114, v116, v117
	v_cvt_pk_bf16_f32 v115, v118, v119
	s_waitcnt lgkmcnt(2)
	v_mfma_f32_32x32x16_bf16 v[80:95], v[204:207], v[148:151], v[80:95]
	v_lshl_add_u32 v208, s42, 14, v185
	ds_read_b64_tr_b16 v[200:201], v208 offset:0
	ds_read_b64_tr_b16 v[202:203], v208 offset:0x800
	ds_read_b64_tr_b16 v[192:193], v208 offset:0x1000
	ds_read_b64_tr_b16 v[194:195], v208 offset:0x1800
	ds_read_b64_tr_b16 v[212:213], v208 offset:0x2000
	ds_read_b64_tr_b16 v[214:215], v208 offset:0x2800
	v_add_f32_e32 v116, v116, v187
	v_add_f32_e32 v117, v117, v191
	v_add_f32_e32 v116, v118, v116
	v_add_f32_e32 v117, v119, v117
	s_waitcnt lgkmcnt(7)
	v_mfma_f32_32x32x16_bf16 v[96:111], v[136:139], v[144:147], v[96:111]
	ds_read_b64_tr_b16 v[204:205], v208 offset:0x3000
	ds_read_b64_tr_b16 v[206:207], v208 offset:0x3800
	ds_read_b64_tr_b16 v[216:217], v208 offset:0x200
	ds_read_b64_tr_b16 v[218:219], v208 offset:0xa00
	v_add_f32_e32 v116, v120, v116
	v_add_f32_e32 v117, v121, v117
	v_add_f32_e32 v187, v122, v116
	v_add_f32_e32 v191, v123, v117
	v_cvt_pk_bf16_f32 v116, v120, v121
	v_cvt_pk_bf16_f32 v117, v122, v123
	v_cvt_pk_bf16_f32 v118, v124, v125
	v_cvt_pk_bf16_f32 v119, v126, v127
	s_waitcnt lgkmcnt(10)
	v_mfma_f32_32x32x16_bf16 v[80:95], v[140:143], v[144:147], v[80:95]
	v_add_f32_e32 v120, v124, v187
	v_add_f32_e32 v121, v125, v191
	v_add_f32_e32 v120, v126, v120
	v_add_f32_e32 v121, v127, v121
	ds_read_b64_tr_b16 v[220:221], v208 offset:0x1200
	ds_read_b64_tr_b16 v[222:223], v208 offset:0x1a00
	ds_read_b64_tr_b16 v[224:225], v208 offset:0x2200
	ds_read_b64_tr_b16 v[226:227], v208 offset:0x2a00
	s_waitcnt lgkmcnt(12)
	v_mfma_f32_32x32x16_bf16 v[48:63], v[128:131], v[200:203], v[48:63]
	v_max_f32_e32 v122, v96, v97
	v_max3_f32 v123, v99, v100, v101
	v_max3_f32 v122, v122, v98, v102
	v_max3_f32 v123, v123, v104, v105
	ds_read_b64_tr_b16 v[200:201], v208 offset:0x3200
	ds_read_b64_tr_b16 v[202:203], v208 offset:0x3a00
	s_waitcnt lgkmcnt(12)
	v_mfma_f32_32x32x16_bf16 v[48:63], v[132:135], v[192:195], v[48:63]
	v_max3_f32 v122, v122, v103, v106
	v_max3_f32 v123, v123, v108, v109
	v_max3_f32 v122, v122, v107, v110
	v_max3_f32 v122, v122, v111, v123
	v_add_f32_e32 v120, v120, v121
	v_mov_b32_e32 v121, v120
	ds_read_b64_tr_b16 v[192:193], v208 offset:0x400
	ds_read_b64_tr_b16 v[194:195], v208 offset:0xc00
	s_waitcnt lgkmcnt(12)
	v_mfma_f32_32x32x16_bf16 v[48:63], v[112:115], v[212:215], v[48:63]
	v_max3_f32 v123, v80, v81, v82
	v_max3_f32 v124, v83, v84, v85
	v_max3_f32 v123, v123, v86, v87
	v_max3_f32 v124, v124, v88, v89
	v_permlane32_swap_b32_e32 v120, v121
	v_max3_f32 v123, v123, v90, v91
	ds_read_b64_tr_b16 v[212:213], v208 offset:0x1400
	ds_read_b64_tr_b16 v[214:215], v208 offset:0x1c00
	s_waitcnt lgkmcnt(12)
	v_mfma_f32_32x32x16_bf16 v[48:63], v[116:119], v[204:207], v[48:63]
	v_max3_f32 v124, v124, v92, v93
	v_max3_f32 v123, v123, v94, v95
	v_max3_f32 v122, v122, v123, v124
	v_mov_b32_e32 v123, v122
	ds_read_b64_tr_b16 v[204:205], v208 offset:0x2400
	ds_read_b64_tr_b16 v[206:207], v208 offset:0x2c00
	s_waitcnt lgkmcnt(12)
	v_mfma_f32_32x32x16_bf16 v[32:47], v[128:131], v[216:219], v[32:47]
	v_permlane32_swap_b32_e32 v122, v123
	v_max_f32_e32 v122, v122, v123
	v_cmp_lt_f32_e32 vcc, s47, v122
	v_mov_b32_e32 v187, 1.0
	s_cbranch_vccnz .LBB0_733
.Lattn_m1_res2:
	ds_read_b64_tr_b16 v[216:217], v208 offset:0x3400
	ds_read_b64_tr_b16 v[218:219], v208 offset:0x3c00
	s_waitcnt lgkmcnt(12)
	v_mfma_f32_32x32x16_bf16 v[32:47], v[132:135], v[220:223], v[32:47]
	v_exp_f32_e32 v96, v96
	v_exp_f32_e32 v97, v97
	v_exp_f32_e32 v98, v98
	ds_read_b64_tr_b16 v[220:221], v208 offset:0x600
	ds_read_b64_tr_b16 v[222:223], v208 offset:0xe00
	s_waitcnt lgkmcnt(12)
	v_mfma_f32_32x32x16_bf16 v[32:47], v[112:115], v[224:227], v[32:47]
	v_exp_f32_e32 v99, v99
	v_exp_f32_e32 v100, v100
	v_exp_f32_e32 v101, v101
	ds_read_b64_tr_b16 v[224:225], v208 offset:0x1600
	ds_read_b64_tr_b16 v[226:227], v208 offset:0x1e00
	s_waitcnt lgkmcnt(12)
	v_mfma_f32_32x32x16_bf16 v[32:47], v[116:119], v[200:203], v[32:47]
	v_exp_f32_e32 v102, v102
	v_exp_f32_e32 v103, v103
	v_exp_f32_e32 v104, v104
	ds_read_b64_tr_b16 v[200:201], v208 offset:0x2600
	ds_read_b64_tr_b16 v[202:203], v208 offset:0x2e00
	s_waitcnt lgkmcnt(12)
	v_mfma_f32_32x32x16_bf16 v[16:31], v[128:131], v[192:195], v[16:31]
	v_exp_f32_e32 v105, v105
	v_exp_f32_e32 v106, v106
	v_exp_f32_e32 v107, v107
	ds_read_b64_tr_b16 v[192:193], v208 offset:0x3600
	ds_read_b64_tr_b16 v[194:195], v208 offset:0x3e00
	s_waitcnt lgkmcnt(12)
	v_mfma_f32_32x32x16_bf16 v[16:31], v[132:135], v[212:215], v[16:31]
	v_exp_f32_e32 v108, v108
	v_exp_f32_e32 v109, v109
	v_exp_f32_e32 v110, v110
	s_waitcnt lgkmcnt(10)
	v_mfma_f32_32x32x16_bf16 v[16:31], v[112:115], v[204:207], v[16:31]
	v_exp_f32_e32 v111, v111
	v_exp_f32_e32 v80, v80
	v_exp_f32_e32 v81, v81
	s_waitcnt lgkmcnt(8)
	v_mfma_f32_32x32x16_bf16 v[16:31], v[116:119], v[216:219], v[16:31]
	v_exp_f32_e32 v82, v82
	v_exp_f32_e32 v83, v83
	v_exp_f32_e32 v84, v84
	s_waitcnt lgkmcnt(6)
	v_mfma_f32_32x32x16_bf16 v[0:15], v[128:131], v[220:223], v[0:15]
	v_exp_f32_e32 v85, v85
	v_exp_f32_e32 v86, v86
	v_exp_f32_e32 v87, v87
	s_waitcnt lgkmcnt(4)
	v_mfma_f32_32x32x16_bf16 v[0:15], v[132:135], v[224:227], v[0:15]
	v_exp_f32_e32 v88, v88
	v_exp_f32_e32 v89, v89
	v_exp_f32_e32 v90, v90
	s_waitcnt lgkmcnt(2)
	v_mfma_f32_32x32x16_bf16 v[0:15], v[112:115], v[200:203], v[0:15]
	v_exp_f32_e32 v91, v91
	v_exp_f32_e32 v92, v92
	v_exp_f32_e32 v93, v93
	s_waitcnt lgkmcnt(0)
	v_mfma_f32_32x32x16_bf16 v[0:15], v[116:119], v[192:195], v[0:15]
	v_exp_f32_e32 v94, v94
	v_exp_f32_e32 v95, v95
	v_cmp_gt_f32_e32 vcc, 1.0, v187
	s_cbranch_vccz .LBB0_730
	s_and_saveexec_b64 s[52:53], s[0:1]
	ds_write_b32 v180, v187 offset:128
	s_or_b64 exec, exec, s[52:53]
	s_waitcnt lgkmcnt(0)
	v_add_u32_e32 v126, s19, v168
	ds_read_b128 v[112:115], v126 offset:224
	ds_read_b128 v[116:119], v126 offset:192
	ds_read_b128 v[122:125], v126 offset:160
	ds_read_b128 v[126:129], v126 offset:128
	s_waitcnt lgkmcnt(3)
	v_pk_mul_f32 v[60:61], v[60:61], v[112:113]
	s_waitcnt lgkmcnt(2)
	v_pk_mul_f32 v[56:57], v[56:57], v[116:117]
	s_waitcnt lgkmcnt(1)
	v_pk_mul_f32 v[52:53], v[52:53], v[122:123]
	v_pk_mul_f32 v[62:63], v[62:63], v[114:115]
	v_pk_mul_f32 v[58:59], v[58:59], v[118:119]
	v_pk_mul_f32 v[54:55], v[54:55], v[124:125]
	s_waitcnt lgkmcnt(0)
	v_pk_mul_f32 v[50:51], v[50:51], v[128:129]
	v_pk_mul_f32 v[48:49], v[48:49], v[126:127]
	v_pk_mul_f32 v[44:45], v[44:45], v[112:113]
	v_pk_mul_f32 v[40:41], v[40:41], v[116:117]
	v_pk_mul_f32 v[36:37], v[36:37], v[122:123]
	v_pk_mul_f32 v[46:47], v[46:47], v[114:115]
	v_pk_mul_f32 v[42:43], v[42:43], v[118:119]
	v_pk_mul_f32 v[38:39], v[38:39], v[124:125]
	v_pk_mul_f32 v[34:35], v[34:35], v[128:129]
	v_pk_mul_f32 v[32:33], v[32:33], v[126:127]
	v_pk_mul_f32 v[28:29], v[28:29], v[112:113]
	v_pk_mul_f32 v[24:25], v[24:25], v[116:117]
	v_pk_mul_f32 v[20:21], v[20:21], v[122:123]
	v_pk_mul_f32 v[30:31], v[30:31], v[114:115]
	v_pk_mul_f32 v[26:27], v[26:27], v[118:119]
	v_pk_mul_f32 v[22:23], v[22:23], v[124:125]
	v_pk_mul_f32 v[18:19], v[18:19], v[128:129]
	v_pk_mul_f32 v[16:17], v[16:17], v[126:127]
	v_pk_mul_f32 v[12:13], v[12:13], v[112:113]
	v_pk_mul_f32 v[8:9], v[8:9], v[116:117]
	v_pk_mul_f32 v[4:5], v[4:5], v[122:123]
	v_pk_mul_f32 v[14:15], v[14:15], v[114:115]
	v_pk_mul_f32 v[10:11], v[10:11], v[118:119]
	v_pk_mul_f32 v[6:7], v[6:7], v[124:125]
	v_pk_mul_f32 v[2:3], v[2:3], v[128:129]
	v_pk_mul_f32 v[0:1], v[0:1], v[126:127]

; __global__ void __launch_bounds__(NTHREADS) fwd_megakernel(Args a) {
	.amdhsa_kernel _Z14fwd_megakernel4Args
		.amdhsa_group_segment_fixed_size 0
		.amdhsa_private_segment_fixed_size 0
		.amdhsa_kernarg_size 496
		.amdhsa_user_sgpr_count 2
		.amdhsa_user_sgpr_dispatch_ptr 0
		.amdhsa_user_sgpr_queue_ptr 0
		.amdhsa_user_sgpr_kernarg_segment_ptr 1
		.amdhsa_user_sgpr_dispatch_id 0
		.amdhsa_user_sgpr_kernarg_preload_length 0
		.amdhsa_user_sgpr_kernarg_preload_offset 0
		.amdhsa_user_sgpr_private_segment_size 0
		.amdhsa_uses_dynamic_stack 0
		.amdhsa_enable_private_segment 0
		.amdhsa_system_sgpr_workgroup_id_x 1
		.amdhsa_system_sgpr_workgroup_id_y 0
		.amdhsa_system_sgpr_workgroup_id_z 0
		.amdhsa_system_sgpr_workgroup_info 0
		.amdhsa_system_vgpr_workitem_id 2
		.amdhsa_next_free_vgpr 239
		.amdhsa_next_free_sgpr 102
		.amdhsa_accum_offset 240
		.amdhsa_reserve_vcc 1
		.amdhsa_float_round_mode_32 0
		.amdhsa_float_round_mode_16_64 0
		.amdhsa_float_denorm_mode_32 3
		.amdhsa_float_denorm_mode_16_64 3
		.amdhsa_dx10_clamp 1
		.amdhsa_ieee_mode 1
		.amdhsa_fp16_overflow 0
		.amdhsa_tg_split 0
		.amdhsa_exception_fp_ieee_invalid_op 0
		.amdhsa_exception_fp_denorm_src 0
		.amdhsa_exception_fp_ieee_div_zero 0
		.amdhsa_exception_fp_ieee_overflow 0
		.amdhsa_exception_fp_ieee_underflow 0
		.amdhsa_exception_fp_ieee_inexact 0
		.amdhsa_exception_int_div_zero 0
	.end_amdhsa_kernel

; __global__ void __launch_bounds__(NTHREADS) fwd_megakernel(Args a) {
amdhsa.kernels:
  - .agpr_count:     0
    .args:
      - .offset:         0
        .size:           240
        .value_kind:     by_value
      - .offset:         240
        .size:           4
        .value_kind:     hidden_block_count_x
      - .offset:         244
        .size:           4
        .value_kind:     hidden_block_count_y
      - .offset:         248
        .size:           4
        .value_kind:     hidden_block_count_z
      - .offset:         252
        .size:           2
        .value_kind:     hidden_group_size_x
      - .offset:         254
        .size:           2
        .value_kind:     hidden_group_size_y
      - .offset:         256
        .size:           2
        .value_kind:     hidden_group_size_z
      - .offset:         258
        .size:           2
        .value_kind:     hidden_remainder_x
      - .offset:         260
        .size:           2
        .value_kind:     hidden_remainder_y
      - .offset:         262
        .size:           2
        .value_kind:     hidden_remainder_z
      - .offset:         280
        .size:           8
        .value_kind:     hidden_global_offset_x
      - .offset:         288
        .size:           8
        .value_kind:     hidden_global_offset_y
      - .offset:         296
        .size:           8
        .value_kind:     hidden_global_offset_z
      - .offset:         304
        .size:           2
        .value_kind:     hidden_grid_dims
      - .offset:         328
        .size:           8
        .value_kind:     hidden_multigrid_sync_arg
      - .offset:         360
        .size:           4
        .value_kind:     hidden_dynamic_lds_size
    .group_segment_fixed_size: 0
    .kernarg_segment_align: 8
    .kernarg_segment_size: 496
    .language:       OpenCL C
    .language_version:
      - 2
      - 0
    .max_flat_workgroup_size: 512
    .name:           _Z14fwd_megakernel4Args
    .private_segment_fixed_size: 0
    .sgpr_count:     108
    .sgpr_spill_count: 35
    .symbol:         _Z14fwd_megakernel4Args.kd
    .uniform_work_group_size: 1
    .uses_dynamic_stack: false
    .vgpr_count:     239
    .vgpr_spill_count: 0
    .wavefront_size: 64
